# adds: next unit's As[1][1] K-tile-1 loads issued at epilogue start, third vmcnt dropped from peeled iteration
# speedup vs baseline: 1.0067x; 1.0004x over previous
; #define PG8_STAGE(bufoff, gbase, voff) do { _Pragma("unroll") for (int _i = 0; _i < 2; ++_i) \
;         __builtin_amdgcn_global_load_lds((const unsigned*)((const char*)(gbase) + (voff)[_i]), (PG8_LAS unsigned*)(lds + (bufoff) + ldsw + _i * 8192), 16, 0, 0); } while (0)
; #define PG8_LDA(dst, b, h) do { _Pragma("unroll") for (int m = 0; m < 4; ++m) _Pragma("unroll") for (int k = 0; k < 2; ++k) dst[m][k] = *(const PG8_LAS bf16x8*)(lds + PG8_SA(b, h) + aoff + m * 2048 + k * 1024); } while (0)
; #define PG8_LDB(dst, b, h) do { _Pragma("unroll") for (int n = 0; n < 2; ++n) _Pragma("unroll") for (int k = 0; k < 2; ++k) dst[n][k] = *(const PG8_LAS bf16x8*)(lds + PG8_SB(b, h) + boff + n * 2048 + k * 1024); } while (0)
; #define PG8_MMA(ai, bj, At, Bt) do { __builtin_amdgcn_s_setprio(1); _Pragma("unroll") for (int m = 0; m < 4; ++m) _Pragma("unroll") for (int n = 0; n < 2; ++n) _Pragma("unroll") for (int k = 0; k < 2; ++k) \
;         acc[ai][bj][m][n] = __builtin_amdgcn_mfma_f32_16x16x32_bf16(Bt[n][k], At[m][k], acc[ai][bj][m][n], 0, 0, 0); __builtin_amdgcn_s_setprio(0); } while (0)
; #define PG8_WAIT_V(n) asm volatile("s_waitcnt vmcnt(" #n ")" ::: "memory")
; #define PG8_WAIT_L(n) asm volatile("s_waitcnt lgkmcnt(" #n ")" ::: "memory")
; #define PG8_BAR __builtin_amdgcn_s_barrier()
; #define PG8_SCHED __builtin_amdgcn_sched_barrier(0)
; template <class Epi, class Sched, bool ALIGN_EPI = false, bool SP2 = false>
; __device__ __forceinline__ void gemm_phase(PG8_LAS unsigned char* lds, const Gemm g, const Sched& S, const Epi& E) {
;     ...
;             PG8_LDB(B0, 0, 0); PG8_LDB(B1, 0, 1); PG8_SCHED; PG8_LDA(At, 0, 0); PG8_STAGE(PG8_SA(1, 1), a1 + hstep, voffA);
;             PG8_WAIT_V(8); PG8_WAIT_L(0); PG8_BAR; PG8_MMA(0, 0, At, B0); PG8_MMA(0, 1, At, B1); PG8_BAR; PG8_SCHED;
;             PG8_LDA(At, 0, 1); PG8_STAGE(PG8_SB(0, 0), b2, voffB); PG8_STAGE(PG8_SB(0, 1), b2 + hstep, voffB); PG8_STAGE(PG8_SA(0, 0), a2, voffA);
;             PG8_WAIT_V(8); PG8_WAIT_L(0); PG8_BAR; PG8_MMA(1, 0, At, B0); PG8_MMA(1, 1, At, B1); PG8_BAR; PG8_SCHED;
.Lpeel_p1:
	s_add_u32 s40, s22, 0xfffc0080
	s_addc_u32 s41, s23, -1
	s_add_i32 s55, 0, 0x10000
	s_cmp_eq_u32 s49, 12
	s_cselect_b32 s61, s5, s41
	s_cselect_b32 s60, s7, s40
	s_cselect_b32 s41, s34, s47
	s_cselect_b32 s40, s35, s45
	s_add_i32 s57, 0, 0x14000
	v_add_u32_e32 v90, s55, v233
	v_add_u32_e32 v110, s57, v233
	ds_read_b128 v[74:77], v90
	ds_read_b128 v[78:81], v90 offset:1024
	ds_read_b128 v[82:85], v90 offset:2048
	ds_read_b128 v[90:93], v90 offset:3072
	ds_read_b128 v[94:97], v110
	ds_read_b128 v[98:101], v110 offset:1024
	ds_read_b128 v[102:105], v110 offset:2048
	ds_read_b128 v[110:113], v110 offset:3072
	v_lshl_add_u64 v[216:217], s[22:23], 0, v[188:189]
	s_add_i32 m0, s66, 0xc000
	ds_read_b128 v[162:165], v234
	ds_read_b128 v[166:169], v234 offset:1024
	ds_read_b128 v[192:195], v234 offset:2048
	ds_read_b128 v[196:199], v234 offset:3072
	ds_read_b128 v[200:203], v234 offset:4096
	ds_read_b128 v[204:207], v234 offset:5120
	ds_read_b128 v[208:211], v234 offset:6144
	ds_read_b128 v[212:215], v234 offset:7168
	v_lshl_add_u64 v[216:217], s[22:23], 0, v[190:191]
	s_add_i32 m0, s66, 0xe000
	s_nop 0
	s_waitcnt lgkmcnt(0)
	s_barrier
	s_setprio 1
	s_waitcnt lgkmcnt(0)
	v_mfma_f32_16x16x32_bf16 v[158:161], v[74:77], v[162:165], v[158:161]
	v_mfma_f32_16x16x32_bf16 v[154:157], v[82:85], v[162:165], v[154:157]
	v_mfma_f32_16x16x32_bf16 v[142:145], v[74:77], v[192:195], v[142:145]
	v_mfma_f32_16x16x32_bf16 v[138:141], v[82:85], v[192:195], v[138:141]
	v_mfma_f32_16x16x32_bf16 v[126:129], v[74:77], v[200:203], v[126:129]
	v_mfma_f32_16x16x32_bf16 v[122:125], v[82:85], v[200:203], v[122:125]
	v_mfma_f32_16x16x32_bf16 v[106:109], v[74:77], v[208:211], v[106:109]
	v_mfma_f32_16x16x32_bf16 v[86:89], v[82:85], v[208:211], v[86:89]
	v_mfma_f32_16x16x32_bf16 v[158:161], v[78:81], v[166:169], v[158:161]
	v_mfma_f32_16x16x32_bf16 v[154:157], v[90:93], v[166:169], v[154:157]
	v_mfma_f32_16x16x32_bf16 v[142:145], v[78:81], v[196:199], v[142:145]
	v_mfma_f32_16x16x32_bf16 v[138:141], v[90:93], v[196:199], v[138:141]
	v_mfma_f32_16x16x32_bf16 v[126:129], v[78:81], v[204:207], v[126:129]
	v_mfma_f32_16x16x32_bf16 v[122:125], v[90:93], v[204:207], v[122:125]
	v_mfma_f32_16x16x32_bf16 v[106:109], v[78:81], v[212:215], v[106:109]
	v_mfma_f32_16x16x32_bf16 v[86:89], v[90:93], v[212:215], v[86:89]
	s_setprio 0
	s_setprio 1
	v_mfma_f32_16x16x32_bf16 v[150:153], v[94:97], v[162:165], v[150:153]
	v_mfma_f32_16x16x32_bf16 v[146:149], v[102:105], v[162:165], v[146:149]
	v_mfma_f32_16x16x32_bf16 v[134:137], v[94:97], v[192:195], v[134:137]
	v_mfma_f32_16x16x32_bf16 v[130:133], v[102:105], v[192:195], v[130:133]
	v_mfma_f32_16x16x32_bf16 v[118:121], v[94:97], v[200:203], v[118:121]
	v_mfma_f32_16x16x32_bf16 v[114:117], v[102:105], v[200:203], v[114:117]
	v_mfma_f32_16x16x32_bf16 v[70:73], v[94:97], v[208:211], v[70:73]
	v_mfma_f32_16x16x32_bf16 v[66:69], v[102:105], v[208:211], v[66:69]
	v_mfma_f32_16x16x32_bf16 v[150:153], v[98:101], v[166:169], v[150:153]
	v_mfma_f32_16x16x32_bf16 v[146:149], v[110:113], v[166:169], v[146:149]
	v_mfma_f32_16x16x32_bf16 v[134:137], v[98:101], v[196:199], v[134:137]
	v_mfma_f32_16x16x32_bf16 v[130:133], v[110:113], v[196:199], v[130:133]
	v_mfma_f32_16x16x32_bf16 v[118:121], v[98:101], v[204:207], v[118:121]
	v_mfma_f32_16x16x32_bf16 v[114:117], v[110:113], v[204:207], v[114:117]
	v_mfma_f32_16x16x32_bf16 v[70:73], v[98:101], v[212:215], v[70:73]
	v_mfma_f32_16x16x32_bf16 v[66:69], v[110:113], v[212:215], v[66:69]
	s_setprio 0
	s_barrier
	s_add_i32 s55, s55, s65
	v_lshl_add_u64 v[216:217], s[40:41], 0, v[0:1]
	s_mov_b32 m0, s55
	ds_read_b128 v[162:165], v234 offset:16384
	ds_read_b128 v[166:169], v234 offset:17408
	ds_read_b128 v[192:195], v234 offset:18432
	ds_read_b128 v[196:199], v234 offset:19456
	ds_read_b128 v[200:203], v234 offset:20480
	ds_read_b128 v[204:207], v234 offset:21504
	ds_read_b128 v[208:211], v234 offset:22528
	ds_read_b128 v[212:215], v234 offset:23552
	global_load_lds_dwordx4 v[216:217], off
	s_add_i32 m0, s55, 0x2000
	s_add_u32 s62, s40, 0x40000
	v_lshl_add_u64 v[218:219], s[40:41], 0, v[186:187]
	s_addc_u32 s63, s41, 0
	s_add_i32 s55, s57, s65
	global_load_lds_dwordx4 v[218:219], off
	v_lshl_add_u64 v[236:237], s[62:63], 0, v[0:1]
	s_mov_b32 m0, s55
	v_lshl_add_u64 v[238:239], s[60:61], 0, v[184:185]
	global_load_lds_dwordx4 v[236:237], off
	v_lshl_add_u64 v[236:237], s[62:63], 0, v[186:187]
	s_add_i32 m0, s55, 0x2000
	s_nop 0
	global_load_lds_dwordx4 v[236:237], off
	v_lshl_add_u64 v[236:237], s[60:61], 0, v[182:183]
	s_mov_b32 m0, s66
	s_nop 0
	global_load_lds_dwordx4 v[236:237], off
	s_mov_b32 m0, s67
	s_nop 0
	global_load_lds_dwordx4 v[238:239], off
	s_waitcnt lgkmcnt(0)
	s_barrier
; #define PG8_STAGE(bufoff, gbase, voff) do { _Pragma("unroll") for (int _i = 0; _i < 2; ++_i) \
;         __builtin_amdgcn_global_load_lds((const unsigned*)((const char*)(gbase) + (voff)[_i]), (PG8_LAS unsigned*)(lds + (bufoff) + ldsw + _i * 8192), 16, 0, 0); } while (0)
; #define PG8_LDA(dst, b, h) do { _Pragma("unroll") for (int m = 0; m < 4; ++m) _Pragma("unroll") for (int k = 0; k < 2; ++k) dst[m][k] = *(const PG8_LAS bf16x8*)(lds + PG8_SA(b, h) + aoff + m * 2048 + k * 1024); } while (0)
; #define PG8_LDB(dst, b, h) do { _Pragma("unroll") for (int n = 0; n < 2; ++n) _Pragma("unroll") for (int k = 0; k < 2; ++k) dst[n][k] = *(const PG8_LAS bf16x8*)(lds + PG8_SB(b, h) + boff + n * 2048 + k * 1024); } while (0)
; #define PG8_MMA(ai, bj, At, Bt) do { __builtin_amdgcn_s_setprio(1); _Pragma("unroll") for (int m = 0; m < 4; ++m) _Pragma("unroll") for (int n = 0; n < 2; ++n) _Pragma("unroll") for (int k = 0; k < 2; ++k) \
;         acc[ai][bj][m][n] = __builtin_amdgcn_mfma_f32_16x16x32_bf16(Bt[n][k], At[m][k], acc[ai][bj][m][n], 0, 0, 0); __builtin_amdgcn_s_setprio(0); } while (0)
; #define PG8_WAIT_V(n) asm volatile("s_waitcnt vmcnt(" #n ")" ::: "memory")
; #define PG8_WAIT_L(n) asm volatile("s_waitcnt lgkmcnt(" #n ")" ::: "memory")
; #define PG8_BAR __builtin_amdgcn_s_barrier()
; #define PG8_SCHED __builtin_amdgcn_sched_barrier(0)
; template <class Epi, class Sched, bool ALIGN_EPI = false, bool SP2 = false>
; __device__ __forceinline__ void gemm_phase(PG8_LAS unsigned char* lds, const Gemm g, const Sched& S, const Epi& E) {
;     ...
;             PG8_WAIT_V(8); PG8_WAIT_L(0); PG8_BAR; PG8_MMA(1, 0, At, B0); PG8_MMA(1, 1, At, B1); PG8_BAR; PG8_SCHED;
;             PG8_LDB(B0, 1, 0); PG8_LDB(B1, 1, 1); PG8_SCHED; PG8_LDA(At, 1, 0); PG8_STAGE(PG8_SA(0, 1), a2 + hstep, voffA);
;             PG8_WAIT_V(8); PG8_WAIT_L(0); PG8_BAR; PG8_MMA(0, 0, At, B0); PG8_MMA(0, 1, At, B1); PG8_BAR; PG8_SCHED;
	s_setprio 1
	s_waitcnt lgkmcnt(0)
	v_mfma_f32_16x16x32_bf16 v[62:65], v[74:77], v[162:165], v[62:65]
	v_mfma_f32_16x16x32_bf16 v[58:61], v[82:85], v[162:165], v[58:61]
	v_mfma_f32_16x16x32_bf16 v[46:49], v[74:77], v[192:195], v[46:49]
	v_mfma_f32_16x16x32_bf16 v[42:45], v[82:85], v[192:195], v[42:45]
	v_mfma_f32_16x16x32_bf16 v[30:33], v[74:77], v[200:203], v[30:33]
	v_mfma_f32_16x16x32_bf16 v[26:29], v[82:85], v[200:203], v[26:29]
	v_mfma_f32_16x16x32_bf16 v[14:17], v[74:77], v[208:211], v[14:17]
	v_mfma_f32_16x16x32_bf16 v[10:13], v[82:85], v[208:211], v[10:13]
	v_mfma_f32_16x16x32_bf16 v[62:65], v[78:81], v[166:169], v[62:65]
	v_mfma_f32_16x16x32_bf16 v[58:61], v[90:93], v[166:169], v[58:61]
	v_mfma_f32_16x16x32_bf16 v[46:49], v[78:81], v[196:199], v[46:49]
	v_mfma_f32_16x16x32_bf16 v[42:45], v[90:93], v[196:199], v[42:45]
	v_mfma_f32_16x16x32_bf16 v[30:33], v[78:81], v[204:207], v[30:33]
	v_mfma_f32_16x16x32_bf16 v[26:29], v[90:93], v[204:207], v[26:29]
	v_mfma_f32_16x16x32_bf16 v[14:17], v[78:81], v[212:215], v[14:17]
	v_mfma_f32_16x16x32_bf16 v[10:13], v[90:93], v[212:215], v[10:13]
	s_setprio 0
	s_setprio 1
	v_mfma_f32_16x16x32_bf16 v[54:57], v[94:97], v[162:165], v[54:57]
	v_mfma_f32_16x16x32_bf16 v[50:53], v[102:105], v[162:165], v[50:53]
	v_mfma_f32_16x16x32_bf16 v[38:41], v[94:97], v[192:195], v[38:41]
	v_mfma_f32_16x16x32_bf16 v[34:37], v[102:105], v[192:195], v[34:37]
	v_mfma_f32_16x16x32_bf16 v[22:25], v[94:97], v[200:203], v[22:25]
	v_mfma_f32_16x16x32_bf16 v[18:21], v[102:105], v[200:203], v[18:21]
	v_mfma_f32_16x16x32_bf16 v[6:9], v[94:97], v[208:211], v[6:9]
	v_mfma_f32_16x16x32_bf16 v[2:5], v[102:105], v[208:211], v[2:5]
	v_mfma_f32_16x16x32_bf16 v[54:57], v[98:101], v[166:169], v[54:57]
	v_mfma_f32_16x16x32_bf16 v[50:53], v[110:113], v[166:169], v[50:53]
	v_mfma_f32_16x16x32_bf16 v[38:41], v[98:101], v[196:199], v[38:41]
	v_mfma_f32_16x16x32_bf16 v[34:37], v[110:113], v[196:199], v[34:37]
	v_mfma_f32_16x16x32_bf16 v[22:25], v[98:101], v[204:207], v[22:25]
	v_mfma_f32_16x16x32_bf16 v[18:21], v[110:113], v[204:207], v[18:21]
	v_mfma_f32_16x16x32_bf16 v[6:9], v[98:101], v[212:215], v[6:9]
	v_mfma_f32_16x16x32_bf16 v[2:5], v[110:113], v[212:215], v[2:5]
	s_setprio 0
	s_barrier
	s_add_i32 s55, 0, 0x18000
	s_add_i32 s57, 0, 0x1c000
	v_add_u32_e32 v90, s55, v233
	v_add_u32_e32 v110, s57, v233
	ds_read_b128 v[74:77], v90
	ds_read_b128 v[78:81], v90 offset:1024
	ds_read_b128 v[82:85], v90 offset:2048
	ds_read_b128 v[90:93], v90 offset:3072
	ds_read_b128 v[94:97], v110
	ds_read_b128 v[98:101], v110 offset:1024
	ds_read_b128 v[102:105], v110 offset:2048
	ds_read_b128 v[110:113], v110 offset:3072
	s_add_u32 s60, s60, 0x40000
	s_addc_u32 s61, s61, 0
	s_mov_b32 m0, s70
	v_lshl_add_u64 v[240:241], s[60:61], 0, v[182:183]
	ds_read_b128 v[162:165], v234 offset:32768
	ds_read_b128 v[166:169], v234 offset:33792
	ds_read_b128 v[192:195], v234 offset:34816
	ds_read_b128 v[196:199], v234 offset:35840
	ds_read_b128 v[200:203], v234 offset:36864
	ds_read_b128 v[204:207], v234 offset:37888
	ds_read_b128 v[208:211], v234 offset:38912
	ds_read_b128 v[212:215], v234 offset:39936
	global_load_lds_dwordx4 v[240:241], off
	v_lshl_add_u64 v[240:241], s[60:61], 0, v[184:185]
	s_mov_b32 m0, s71
	s_nop 0
	global_load_lds_dwordx4 v[240:241], off
	s_waitcnt lgkmcnt(0)
	s_barrier
	s_setprio 1
	s_waitcnt lgkmcnt(0)
	v_mfma_f32_16x16x32_bf16 v[158:161], v[74:77], v[162:165], v[158:161]
	v_mfma_f32_16x16x32_bf16 v[154:157], v[82:85], v[162:165], v[154:157]
	v_mfma_f32_16x16x32_bf16 v[142:145], v[74:77], v[192:195], v[142:145]
	v_mfma_f32_16x16x32_bf16 v[138:141], v[82:85], v[192:195], v[138:141]
	v_mfma_f32_16x16x32_bf16 v[126:129], v[74:77], v[200:203], v[126:129]
	v_mfma_f32_16x16x32_bf16 v[122:125], v[82:85], v[200:203], v[122:125]
	v_mfma_f32_16x16x32_bf16 v[106:109], v[74:77], v[208:211], v[106:109]
	v_mfma_f32_16x16x32_bf16 v[86:89], v[82:85], v[208:211], v[86:89]
	v_mfma_f32_16x16x32_bf16 v[158:161], v[78:81], v[166:169], v[158:161]
	v_mfma_f32_16x16x32_bf16 v[154:157], v[90:93], v[166:169], v[154:157]
	v_mfma_f32_16x16x32_bf16 v[142:145], v[78:81], v[196:199], v[142:145]
	v_mfma_f32_16x16x32_bf16 v[138:141], v[90:93], v[196:199], v[138:141]
	v_mfma_f32_16x16x32_bf16 v[126:129], v[78:81], v[204:207], v[126:129]
	v_mfma_f32_16x16x32_bf16 v[122:125], v[90:93], v[204:207], v[122:125]
	v_mfma_f32_16x16x32_bf16 v[106:109], v[78:81], v[212:215], v[106:109]
	v_mfma_f32_16x16x32_bf16 v[86:89], v[90:93], v[212:215], v[86:89]
	s_setprio 0
	s_setprio 1
	v_mfma_f32_16x16x32_bf16 v[150:153], v[94:97], v[162:165], v[150:153]
	v_mfma_f32_16x16x32_bf16 v[146:149], v[102:105], v[162:165], v[146:149]
	v_mfma_f32_16x16x32_bf16 v[134:137], v[94:97], v[192:195], v[134:137]
	v_mfma_f32_16x16x32_bf16 v[130:133], v[102:105], v[192:195], v[130:133]
	v_mfma_f32_16x16x32_bf16 v[118:121], v[94:97], v[200:203], v[118:121]
	v_mfma_f32_16x16x32_bf16 v[114:117], v[102:105], v[200:203], v[114:117]
	v_mfma_f32_16x16x32_bf16 v[70:73], v[94:97], v[208:211], v[70:73]
	v_mfma_f32_16x16x32_bf16 v[66:69], v[102:105], v[208:211], v[66:69]
	v_mfma_f32_16x16x32_bf16 v[150:153], v[98:101], v[166:169], v[150:153]
	v_mfma_f32_16x16x32_bf16 v[146:149], v[110:113], v[166:169], v[146:149]
	v_mfma_f32_16x16x32_bf16 v[134:137], v[98:101], v[196:199], v[134:137]
	v_mfma_f32_16x16x32_bf16 v[130:133], v[110:113], v[196:199], v[130:133]
	v_mfma_f32_16x16x32_bf16 v[118:121], v[98:101], v[204:207], v[118:121]
	v_mfma_f32_16x16x32_bf16 v[114:117], v[110:113], v[204:207], v[114:117]
	v_mfma_f32_16x16x32_bf16 v[70:73], v[98:101], v[212:215], v[70:73]
	v_mfma_f32_16x16x32_bf16 v[66:69], v[110:113], v[212:215], v[66:69]
	s_setprio 0
	s_barrier
; #define PG8_STAGE(bufoff, gbase, voff) do { _Pragma("unroll") for (int _i = 0; _i < 2; ++_i) \
;         __builtin_amdgcn_global_load_lds((const unsigned*)((const char*)(gbase) + (voff)[_i]), (PG8_LAS unsigned*)(lds + (bufoff) + ldsw + _i * 8192), 16, 0, 0); } while (0)
; #define PG8_LDA(dst, b, h) do { _Pragma("unroll") for (int m = 0; m < 4; ++m) _Pragma("unroll") for (int k = 0; k < 2; ++k) dst[m][k] = *(const PG8_LAS bf16x8*)(lds + PG8_SA(b, h) + aoff + m * 2048 + k * 1024); } while (0)
; #define PG8_MMA(ai, bj, At, Bt) do { __builtin_amdgcn_s_setprio(1); _Pragma("unroll") for (int m = 0; m < 4; ++m) _Pragma("unroll") for (int n = 0; n < 2; ++n) _Pragma("unroll") for (int k = 0; k < 2; ++k) \
;         acc[ai][bj][m][n] = __builtin_amdgcn_mfma_f32_16x16x32_bf16(Bt[n][k], At[m][k], acc[ai][bj][m][n], 0, 0, 0); __builtin_amdgcn_s_setprio(0); } while (0)
; #define PG8_WAIT_V(n) asm volatile("s_waitcnt vmcnt(" #n ")" ::: "memory")
; #define PG8_WAIT_L(n) asm volatile("s_waitcnt lgkmcnt(" #n ")" ::: "memory")
; #define PG8_BAR __builtin_amdgcn_s_barrier()
; #define PG8_SCHED __builtin_amdgcn_sched_barrier(0)
; template <class Epi, class Sched, bool ALIGN_EPI = false, bool SP2 = false>
; __device__ __forceinline__ void gemm_phase(PG8_LAS unsigned char* lds, const Gemm g, const Sched& S, const Epi& E) {
;     ...
;             PG8_LDA(At, 1, 1); PG8_STAGE(PG8_SB(1, 0), b3, voffB); PG8_STAGE(PG8_SB(1, 1), b3 + hstep, voffB); PG8_STAGE(PG8_SA(1, 0), a3, voffA);
;             PG8_WAIT_V(8); PG8_WAIT_L(0); PG8_BAR; PG8_MMA(1, 0, At, B0); PG8_MMA(1, 1, At, B1); PG8_BAR; PG8_SCHED;
	s_add_i32 s55, s55, s65
	v_lshl_add_u64 v[216:217], v[216:217], 0, s[36:37]
	s_mov_b32 m0, s55
	ds_read_b128 v[162:165], v234 offset:49152
	ds_read_b128 v[166:169], v234 offset:50176
	ds_read_b128 v[192:195], v234 offset:51200
	ds_read_b128 v[196:199], v234 offset:52224
	ds_read_b128 v[200:203], v234 offset:53248
	ds_read_b128 v[204:207], v234 offset:54272
	ds_read_b128 v[208:211], v234 offset:55296
	ds_read_b128 v[212:215], v234 offset:56320
	global_load_lds_dwordx4 v[216:217], off
	s_add_i32 m0, s55, 0x2000
	s_add_u32 s40, s40, 0x40080
	v_lshl_add_u64 v[216:217], v[218:219], 0, s[36:37]
	s_addc_u32 s41, s41, 0
	s_add_i32 s55, s57, s65
	global_load_lds_dwordx4 v[216:217], off
	v_lshl_add_u64 v[216:217], s[40:41], 0, v[0:1]
	s_mov_b32 m0, s55
	s_nop 0
	global_load_lds_dwordx4 v[216:217], off
	v_lshl_add_u64 v[216:217], s[40:41], 0, v[186:187]
	s_add_i32 m0, s55, 0x2000
	s_nop 0
	global_load_lds_dwordx4 v[216:217], off
	v_lshl_add_u64 v[216:217], v[236:237], 0, s[36:37]
	s_mov_b32 m0, s76
	s_nop 0
	global_load_lds_dwordx4 v[216:217], off
	v_lshl_add_u64 v[216:217], v[238:239], 0, s[36:37]
	s_mov_b32 m0, s77
	s_nop 0
	global_load_lds_dwordx4 v[216:217], off
	s_waitcnt vmcnt(8)
	s_waitcnt lgkmcnt(0)
	s_barrier
	s_setprio 1
	s_waitcnt lgkmcnt(0)
	v_mfma_f32_16x16x32_bf16 v[62:65], v[74:77], v[162:165], v[62:65]
	v_mfma_f32_16x16x32_bf16 v[58:61], v[82:85], v[162:165], v[58:61]
	v_mfma_f32_16x16x32_bf16 v[46:49], v[74:77], v[192:195], v[46:49]
	v_mfma_f32_16x16x32_bf16 v[42:45], v[82:85], v[192:195], v[42:45]
	v_mfma_f32_16x16x32_bf16 v[30:33], v[74:77], v[200:203], v[30:33]
	v_mfma_f32_16x16x32_bf16 v[26:29], v[82:85], v[200:203], v[26:29]
	v_mfma_f32_16x16x32_bf16 v[14:17], v[74:77], v[208:211], v[14:17]
	v_mfma_f32_16x16x32_bf16 v[10:13], v[82:85], v[208:211], v[10:13]
	v_mfma_f32_16x16x32_bf16 v[62:65], v[78:81], v[166:169], v[62:65]
	v_mfma_f32_16x16x32_bf16 v[58:61], v[90:93], v[166:169], v[58:61]
	v_mfma_f32_16x16x32_bf16 v[46:49], v[78:81], v[196:199], v[46:49]
	v_mfma_f32_16x16x32_bf16 v[42:45], v[90:93], v[196:199], v[42:45]
	v_mfma_f32_16x16x32_bf16 v[30:33], v[78:81], v[204:207], v[30:33]
	v_mfma_f32_16x16x32_bf16 v[26:29], v[90:93], v[204:207], v[26:29]
	v_mfma_f32_16x16x32_bf16 v[14:17], v[78:81], v[212:215], v[14:17]
	v_mfma_f32_16x16x32_bf16 v[10:13], v[90:93], v[212:215], v[10:13]
	s_setprio 0
	s_setprio 1
	v_mfma_f32_16x16x32_bf16 v[54:57], v[94:97], v[162:165], v[54:57]
	v_mfma_f32_16x16x32_bf16 v[50:53], v[102:105], v[162:165], v[50:53]
	v_mfma_f32_16x16x32_bf16 v[38:41], v[94:97], v[192:195], v[38:41]
	v_mfma_f32_16x16x32_bf16 v[34:37], v[102:105], v[192:195], v[34:37]
	v_mfma_f32_16x16x32_bf16 v[22:25], v[94:97], v[200:203], v[22:25]
	v_mfma_f32_16x16x32_bf16 v[18:21], v[102:105], v[200:203], v[18:21]
	v_mfma_f32_16x16x32_bf16 v[6:9], v[94:97], v[208:211], v[6:9]
	v_mfma_f32_16x16x32_bf16 v[2:5], v[102:105], v[208:211], v[2:5]
	v_mfma_f32_16x16x32_bf16 v[54:57], v[98:101], v[166:169], v[54:57]
	v_mfma_f32_16x16x32_bf16 v[50:53], v[110:113], v[166:169], v[50:53]
	v_mfma_f32_16x16x32_bf16 v[38:41], v[98:101], v[196:199], v[38:41]
	v_mfma_f32_16x16x32_bf16 v[34:37], v[110:113], v[196:199], v[34:37]
	v_mfma_f32_16x16x32_bf16 v[22:25], v[98:101], v[204:207], v[22:25]
	v_mfma_f32_16x16x32_bf16 v[18:21], v[110:113], v[204:207], v[18:21]
	v_mfma_f32_16x16x32_bf16 v[6:9], v[98:101], v[212:215], v[6:9]
	v_mfma_f32_16x16x32_bf16 v[2:5], v[110:113], v[212:215], v[2:5]
	s_setprio 0
	s_barrier
	s_add_i32 s49, s49, 2
	s_add_u32 s22, s22, 0x100
	s_addc_u32 s23, s23, 0
	s_add_u32 s45, s45, 0x100
	s_addc_u32 s47, s47, 0
	s_cmp_gt_u32 s49, 13
	s_cbranch_scc0 .LBB0_157
	s_branch .Lafter_157

; #define PG8_STAGE(bufoff, gbase, voff) do { _Pragma("unroll") for (int _i = 0; _i < 2; ++_i) \
;         __builtin_amdgcn_global_load_lds((const unsigned*)((const char*)(gbase) + (voff)[_i]), (PG8_LAS unsigned*)(lds + (bufoff) + ldsw + _i * 8192), 16, 0, 0); } while (0)
; #define PG8_LDA(dst, b, h) do { _Pragma("unroll") for (int m = 0; m < 4; ++m) _Pragma("unroll") for (int k = 0; k < 2; ++k) dst[m][k] = *(const PG8_LAS bf16x8*)(lds + PG8_SA(b, h) + aoff + m * 2048 + k * 1024); } while (0)
; #define PG8_LDB(dst, b, h) do { _Pragma("unroll") for (int n = 0; n < 2; ++n) _Pragma("unroll") for (int k = 0; k < 2; ++k) dst[n][k] = *(const PG8_LAS bf16x8*)(lds + PG8_SB(b, h) + boff + n * 2048 + k * 1024); } while (0)
; #define PG8_BAR __builtin_amdgcn_s_barrier()
; #define PG8_SCHED __builtin_amdgcn_sched_barrier(0)
; template <class Epi, class Sched, bool ALIGN_EPI = false, bool SP2 = false>
; __device__ __forceinline__ void gemm_phase(PG8_LAS unsigned char* lds, const Gemm g, const Sched& S, const Epi& E) {
;     ...
;             if (last && has_next) S.a_ready(nxt);
;             if constexpr (SP2) {
;             PG8_LDB(B0, 0, 0); PG8_LDB(B1, 0, 1); PG8_SCHED; PG8_LDA(At, 0, 0); PG8_STAGE(PG8_SA(1, 1), a1 + hstep, voffA);
;     ...
;         if constexpr (ALIGN_EPI) { if (wr == 0) PG8_BAR; }
;         if constexpr (!Epi::AFTER_DRAIN) { E(acc, cur, wr, wc, fr, fq); S.done(cur); }
.LBB0_160:
	s_and_b64 vcc, exec, s[42:43]
	s_cbranch_vccz .Lno_early_p1
	s_add_u32 s98, s50, 0x40080
	s_addc_u32 s99, s51, 0
	v_lshl_add_u64 v[216:217], s[98:99], 0, v[188:189]
	s_add_i32 m0, s66, 0xc000
	s_nop 0
	global_load_lds_dwordx4 v[216:217], off
	v_lshl_add_u64 v[216:217], s[98:99], 0, v[190:191]
	s_add_i32 m0, s66, 0xe000
	s_nop 0
	global_load_lds_dwordx4 v[216:217], off
